# attention-tile epilogue rope: lane^16 partner by in-place v_permlane16_swap instead of ds_bpermute, and the two lane-divergent arms replaced by a branch-free form with the same roundings (sign bit of
# speedup vs baseline: 1.0114x; 1.0114x over previous
.LBB0_309:
	s_waitcnt vmcnt(0)
	s_cmp_lt_u32 s44, 12
	s_cselect_b64 s[4:5], -1, 0
	s_add_i32 s6, s57, 0xfffff200
	s_cmpk_lt_u32 s6, 0x280
	s_cselect_b64 s[6:7], -1, 0
	s_or_b64 s[4:5], s[4:5], s[6:7]
	s_and_b64 s[4:5], s[70:71], s[4:5]
	v_cndmask_b32_e64 v177, 0, 1, s[4:5]
	v_pk_mul_f32 v[128:129], v[128:129], v[216:217] op_sel_hi:[1,0]
	v_pk_mul_f32 v[126:127], v[126:127], v[216:217] op_sel_hi:[1,0]
	v_pk_mul_f32 v[124:125], v[124:125], v[216:217] op_sel_hi:[1,0]
	v_cmp_ne_u32_e64 s[42:43], 1, v177
	s_andn2_b64 vcc, exec, s[4:5]
	v_pk_mul_f32 v[122:123], v[122:123], v[216:217] op_sel_hi:[1,0]
	s_cbranch_vccnz .LBB0_335
	v_and_b32_e32 v193, 64, v226
	v_xor_b32_e32 v177, 16, v226
	v_add_u32_e32 v193, 64, v193
	v_cmp_lt_i32_e32 vcc, v177, v193
	s_nop 1
	v_cndmask_b32_e32 v177, v226, v177, vcc
	v_lshlrev_b32_e32 v177, 2, v177
	v_mov_b32_e32 v221, v126
	v_mov_b32_e32 v219, v122
	s_nop 0
	v_permlane16_swap_b32 v221, v221
	v_permlane16_swap_b32 v219, v219
	v_cmp_lt_i32_e64 s[4:5], 1, v233
	v_cmp_eq_u32_e64 s[6:7], 1, v233
	v_bfrev_b32_e32 v239, 1
	s_nop 0
	v_cndmask_b32_e64 v239, v239, 0, s[6:7]
	v_mul_f32_e32 v220, v126, v158
	v_mul_f32_e32 v221, v154, v221
	v_xor_b32_e32 v221, v239, v221
	v_add_f32_e32 v220, v220, v221
	v_cndmask_b32_e64 v126, v220, v126, s[4:5]
	v_mul_f32_e32 v218, v122, v150
	v_mul_f32_e32 v219, v146, v219
	v_xor_b32_e32 v219, v239, v219
	v_add_f32_e32 v218, v218, v219
	v_cndmask_b32_e64 v122, v218, v122, s[4:5]
	s_waitcnt lgkmcnt(0)
	v_mov_b32_e32 v221, v127
	v_mov_b32_e32 v219, v123
	s_nop 0
	v_permlane16_swap_b32 v221, v221
	v_permlane16_swap_b32 v219, v219
	v_cmp_lt_i32_e64 s[4:5], 1, v233
	v_cmp_eq_u32_e64 s[6:7], 1, v233
	v_bfrev_b32_e32 v239, 1
	s_nop 0
	v_cndmask_b32_e64 v239, v239, 0, s[6:7]
	v_mul_f32_e32 v218, v159, v127
	v_xor_b32_e32 v238, v239, v155
	v_fma_f32 v221, v238, v221, v218
	v_cndmask_b32_e64 v127, v221, v127, s[4:5]
	v_mul_f32_e32 v220, v151, v123
	v_xor_b32_e32 v238, v239, v147
	v_fma_f32 v219, v238, v219, v220
	v_cndmask_b32_e64 v123, v219, v123, s[4:5]
	s_waitcnt lgkmcnt(0)
	v_mov_b32_e32 v221, v128
	v_mov_b32_e32 v219, v124
	s_nop 0
	v_permlane16_swap_b32 v221, v221
	v_permlane16_swap_b32 v219, v219
	v_cmp_lt_i32_e64 s[4:5], 1, v233
	v_cmp_eq_u32_e64 s[6:7], 1, v233
	v_bfrev_b32_e32 v239, 1
	s_nop 0
	v_cndmask_b32_e64 v239, v239, 0, s[6:7]
	v_mul_f32_e32 v221, v156, v221
	v_xor_b32_e32 v221, v239, v221
	v_fma_f32 v220, v160, v128, v221
	v_cndmask_b32_e64 v128, v220, v128, s[4:5]
	v_mul_f32_e32 v219, v148, v219
	v_xor_b32_e32 v219, v239, v219
	v_fma_f32 v218, v152, v124, v219
	v_cndmask_b32_e64 v124, v218, v124, s[4:5]
	s_waitcnt lgkmcnt(0)
	v_mov_b32_e32 v221, v129
	v_mov_b32_e32 v219, v125
	s_nop 0
	v_permlane16_swap_b32 v221, v221
	v_permlane16_swap_b32 v219, v219
	v_cmp_lt_i32_e64 s[4:5], 1, v233
	v_cmp_eq_u32_e64 s[6:7], 1, v233
	v_bfrev_b32_e32 v239, 1
	s_nop 0
	v_cndmask_b32_e64 v239, v239, 0, s[6:7]
	v_mul_f32_e32 v221, v157, v221
	v_xor_b32_e32 v221, v239, v221
	v_fma_f32 v220, v161, v129, v221
	v_cndmask_b32_e64 v129, v220, v129, s[4:5]
	v_mul_f32_e32 v219, v149, v219
	v_xor_b32_e32 v219, v239, v219
	v_fma_f32 v218, v153, v125, v219
	v_cndmask_b32_e64 v125, v218, v125, s[4:5]
.LBB0_335:
	s_and_b32 s4, s44, 30
	s_cmp_eq_u32 s4, 14
	s_cselect_b64 s[4:5], -1, 0
	s_cmp_lt_u32 s44, 10
	s_cselect_b64 s[6:7], -1, 0
	s_waitcnt lgkmcnt(0)
	v_pk_mul_f32 v[218:219], v[126:127], s[36:37] op_sel_hi:[1,0]
	v_pk_mul_f32 v[238:239], v[122:123], s[36:37] op_sel_hi:[1,0]
	s_or_b64 s[40:41], s[6:7], s[4:5]
	v_pk_mul_f32 v[220:221], v[128:129], s[36:37] op_sel_hi:[1,0]
	v_pk_mul_f32 v[240:241], v[124:125], s[36:37] op_sel_hi:[1,0]
	v_cndmask_b32_e64 v126, v126, v218, s[40:41]
	v_cndmask_b32_e64 v122, v122, v238, s[40:41]
	v_cndmask_b32_e64 v123, v123, v239, s[40:41]
	v_cndmask_b32_e64 v128, v128, v220, s[40:41]
	v_cndmask_b32_e64 v129, v129, v221, s[40:41]
	v_cndmask_b32_e64 v127, v127, v219, s[40:41]
	v_cndmask_b32_e64 v177, v124, v240, s[40:41]
	v_cndmask_b32_e64 v193, v125, v241, s[40:41]
	v_cvt_pk_bf16_f32 v124, v126, v127
	v_cvt_pk_bf16_f32 v125, v128, v129
	v_cvt_pk_bf16_f32 v126, v122, v123
	v_mov_b64_e32 v[122:123], s[62:63]
	s_movk_i32 s6, 0x1200
	v_mad_i64_i32 v[122:123], s[6:7], v214, s6, v[122:123]
	s_or_b32 s8, s57, 0x80
	v_lshl_add_u64 v[128:129], v[0:1], 1, v[122:123]
	s_movk_i32 s6, 0xf000
	s_cmpk_lt_i32 s8, 0xc00
	v_add_co_u32_e32 v128, vcc, s6, v128
	s_cselect_b64 s[6:7], -1, 0
	s_add_i32 s10, s57, 0xfffff280
	s_cmpk_lt_u32 s10, 0x280
	s_cselect_b64 s[10:11], -1, 0
	v_addc_co_u32_e32 v129, vcc, -1, v129, vcc
	s_or_b64 s[6:7], s[6:7], s[10:11]
	v_cvt_pk_bf16_f32 v127, v177, v193
	flat_store_dwordx4 v[128:129], v[124:127] nt
	s_and_b64 s[6:7], s[70:71], s[6:7]
	v_mov_b32_e32 v217, v216
	v_mov_b32_e32 v124, v216
	v_mov_b32_e32 v125, v216
	v_pk_mul_f32 v[120:121], v[120:121], v[124:125]
	v_pk_mul_f32 v[116:117], v[116:117], v[124:125]
	v_cndmask_b32_e64 v124, 0, 1, s[6:7]
	v_pk_mul_f32 v[118:119], v[118:119], v[216:217]
	v_cmp_ne_u32_e64 s[46:47], 1, v124
	s_andn2_b64 vcc, exec, s[6:7]
	v_pk_mul_f32 v[114:115], v[114:115], v[216:217]
	s_cbranch_vccnz .LBB0_361
	v_and_b32_e32 v125, 64, v226
	v_xor_b32_e32 v124, 16, v226
	v_add_u32_e32 v125, 64, v125
	v_cmp_lt_i32_e32 vcc, v124, v125
	s_nop 1
	v_cndmask_b32_e32 v124, v226, v124, vcc
	v_lshlrev_b32_e32 v128, 2, v124
	v_mov_b32_e32 v127, v118
	v_mov_b32_e32 v125, v114
	s_nop 0
	v_permlane16_swap_b32 v127, v127
	v_permlane16_swap_b32 v125, v125
	v_cmp_lt_i32_e64 s[6:7], 1, v233
	v_cmp_eq_u32_e64 s[44:45], 1, v233
	v_bfrev_b32_e32 v239, 1
	s_nop 0
	v_cndmask_b32_e64 v239, v239, 0, s[44:45]
	v_mul_f32_e32 v126, v118, v158
	v_mul_f32_e32 v127, v154, v127
	v_xor_b32_e32 v127, v239, v127
	v_add_f32_e32 v126, v126, v127
	v_cndmask_b32_e64 v118, v126, v118, s[6:7]
	v_mul_f32_e32 v124, v114, v150
	v_mul_f32_e32 v125, v146, v125
	v_xor_b32_e32 v125, v239, v125
	v_add_f32_e32 v124, v124, v125
	v_cndmask_b32_e64 v114, v124, v114, s[6:7]
	s_waitcnt lgkmcnt(0)
	v_mov_b32_e32 v127, v119
	v_mov_b32_e32 v125, v115
	s_nop 0
	v_permlane16_swap_b32 v127, v127
	v_permlane16_swap_b32 v125, v125
	v_cmp_lt_i32_e64 s[6:7], 1, v233
	v_cmp_eq_u32_e64 s[44:45], 1, v233
	v_bfrev_b32_e32 v239, 1
	s_nop 0
	v_cndmask_b32_e64 v239, v239, 0, s[44:45]
	v_mul_f32_e32 v124, v159, v119
	v_xor_b32_e32 v238, v239, v155
	v_fma_f32 v127, v238, v127, v124
	v_cndmask_b32_e64 v119, v127, v119, s[6:7]
	v_mul_f32_e32 v126, v151, v115
	v_xor_b32_e32 v238, v239, v147
	v_fma_f32 v125, v238, v125, v126
	v_cndmask_b32_e64 v115, v125, v115, s[6:7]
	s_waitcnt lgkmcnt(0)
	v_mov_b32_e32 v127, v120
	v_mov_b32_e32 v125, v116
	s_nop 0
	v_permlane16_swap_b32 v127, v127
	v_permlane16_swap_b32 v125, v125
	v_cmp_lt_i32_e64 s[6:7], 1, v233
	v_cmp_eq_u32_e64 s[44:45], 1, v233
	v_bfrev_b32_e32 v239, 1
	s_nop 0
	v_cndmask_b32_e64 v239, v239, 0, s[44:45]
	v_mul_f32_e32 v127, v156, v127
	v_xor_b32_e32 v127, v239, v127
	v_fma_f32 v126, v160, v120, v127
	v_cndmask_b32_e64 v120, v126, v120, s[6:7]
	v_mul_f32_e32 v125, v148, v125
	v_xor_b32_e32 v125, v239, v125
	v_fma_f32 v124, v152, v116, v125
	v_cndmask_b32_e64 v116, v124, v116, s[6:7]
	s_waitcnt lgkmcnt(0)
	v_mov_b32_e32 v127, v121
	v_mov_b32_e32 v125, v117
	s_nop 0
	v_permlane16_swap_b32 v127, v127
	v_permlane16_swap_b32 v125, v125
	v_cmp_lt_i32_e64 s[6:7], 1, v233
	v_cmp_eq_u32_e64 s[44:45], 1, v233
	v_bfrev_b32_e32 v239, 1
	s_nop 0
	v_cndmask_b32_e64 v239, v239, 0, s[44:45]
	v_mul_f32_e32 v127, v157, v127
	v_xor_b32_e32 v127, v239, v127
	v_fma_f32 v126, v161, v121, v127
	v_cndmask_b32_e64 v121, v126, v121, s[6:7]
	v_mul_f32_e32 v125, v149, v125
	v_xor_b32_e32 v125, v239, v125
	v_fma_f32 v124, v153, v117, v125
	v_cndmask_b32_e64 v117, v124, v117, s[6:7]
.LBB0_361:
	s_cmpk_lt_i32 s8, 0xa00
	s_cselect_b64 s[6:7], -1, 0
	s_waitcnt lgkmcnt(0)
	v_pk_mul_f32 v[124:125], v[118:119], s[36:37] op_sel_hi:[1,0]
	v_pk_mul_f32 v[214:215], v[116:117], s[36:37] op_sel_hi:[1,0]
	s_or_b64 s[44:45], s[6:7], s[4:5]
	v_pk_mul_f32 v[128:129], v[114:115], s[36:37] op_sel_hi:[1,0]
	v_cndmask_b32_e64 v118, v118, v124, s[44:45]
	v_cndmask_b32_e64 v119, v119, v125, s[44:45]
	v_cndmask_b32_e64 v124, v116, v214, s[44:45]
	v_cndmask_b32_e64 v117, v117, v215, s[44:45]
	v_add_u32_e32 v214, s57, v236
	v_mov_b32_e32 v215, v1
	v_cndmask_b32_e64 v116, v114, v128, s[44:45]
	v_cvt_pk_bf16_f32 v114, v118, v119
	v_lshl_add_u64 v[118:119], v[214:215], 1, v[122:123]
	s_movk_i32 s4, 0xf100
	v_add_co_u32_e32 v118, vcc, s4, v118
	v_pk_mul_f32 v[126:127], v[120:121], s[36:37] op_sel_hi:[1,0]
	s_nop 0
	v_addc_co_u32_e32 v119, vcc, -1, v119, vcc
	v_pk_mul_f32 v[112:113], v[112:113], v[212:213] op_sel_hi:[1,0]
	v_pk_mul_f32 v[110:111], v[110:111], v[212:213] op_sel_hi:[1,0]
	v_pk_mul_f32 v[108:109], v[108:109], v[212:213] op_sel_hi:[1,0]
	s_and_b64 vcc, exec, s[42:43]
	v_pk_mul_f32 v[106:107], v[106:107], v[212:213] op_sel_hi:[1,0]
	v_cndmask_b32_e64 v120, v120, v126, s[44:45]
	v_cndmask_b32_e64 v121, v121, v127, s[44:45]
	v_cndmask_b32_e64 v125, v115, v129, s[44:45]
	v_cvt_pk_bf16_f32 v115, v120, v121
	v_cvt_pk_bf16_f32 v116, v116, v125
	v_cvt_pk_bf16_f32 v117, v124, v117
	flat_store_dwordx4 v[118:119], v[114:117] nt
	s_cbranch_vccnz .LBB0_387
	s_nop 0
	v_and_b32_e32 v115, 64, v226
	v_xor_b32_e32 v114, 16, v226
	v_add_u32_e32 v115, 64, v115
	v_cmp_lt_i32_e32 vcc, v114, v115
	s_nop 1
	v_cndmask_b32_e32 v114, v226, v114, vcc
	v_lshlrev_b32_e32 v118, 2, v114
	v_mov_b32_e32 v117, v110
	v_mov_b32_e32 v115, v106
	s_nop 0
	v_permlane16_swap_b32 v117, v117
	v_permlane16_swap_b32 v115, v115
	v_cmp_lt_i32_e64 s[4:5], 1, v233
	v_cmp_eq_u32_e64 s[6:7], 1, v233
	v_bfrev_b32_e32 v239, 1
	s_nop 0
	v_cndmask_b32_e64 v239, v239, 0, s[6:7]
	v_mul_f32_e32 v116, v110, v142
	v_mul_f32_e32 v117, v138, v117
	v_xor_b32_e32 v117, v239, v117
	v_add_f32_e32 v116, v116, v117
	v_cndmask_b32_e64 v110, v116, v110, s[4:5]
	v_mul_f32_e32 v114, v106, v134
	v_mul_f32_e32 v115, v130, v115
	v_xor_b32_e32 v115, v239, v115
	v_add_f32_e32 v114, v114, v115
	v_cndmask_b32_e64 v106, v114, v106, s[4:5]
	s_waitcnt lgkmcnt(0)
	v_mov_b32_e32 v117, v111
	v_mov_b32_e32 v115, v107
	s_nop 0
	v_permlane16_swap_b32 v117, v117
	v_permlane16_swap_b32 v115, v115
	v_cmp_lt_i32_e64 s[4:5], 1, v233
	v_cmp_eq_u32_e64 s[6:7], 1, v233
	v_bfrev_b32_e32 v239, 1
	s_nop 0
	v_cndmask_b32_e64 v239, v239, 0, s[6:7]
	v_mul_f32_e32 v114, v143, v111
	v_xor_b32_e32 v238, v239, v139
	v_fma_f32 v117, v238, v117, v114
	v_cndmask_b32_e64 v111, v117, v111, s[4:5]
	v_mul_f32_e32 v116, v135, v107
	v_xor_b32_e32 v238, v239, v131
	v_fma_f32 v115, v238, v115, v116
	v_cndmask_b32_e64 v107, v115, v107, s[4:5]
	s_waitcnt lgkmcnt(0)
	v_mov_b32_e32 v117, v112
	v_mov_b32_e32 v115, v108
	s_nop 0
	v_permlane16_swap_b32 v117, v117
	v_permlane16_swap_b32 v115, v115
	v_cmp_lt_i32_e64 s[4:5], 1, v233
	v_cmp_eq_u32_e64 s[6:7], 1, v233
	v_bfrev_b32_e32 v239, 1
	s_nop 0
	v_cndmask_b32_e64 v239, v239, 0, s[6:7]
	v_mul_f32_e32 v117, v140, v117
	v_xor_b32_e32 v117, v239, v117
	v_fma_f32 v116, v144, v112, v117
	v_cndmask_b32_e64 v112, v116, v112, s[4:5]
	v_mul_f32_e32 v115, v132, v115
	v_xor_b32_e32 v115, v239, v115
	v_fma_f32 v114, v136, v108, v115
	v_cndmask_b32_e64 v108, v114, v108, s[4:5]
	s_waitcnt lgkmcnt(0)
	v_mov_b32_e32 v117, v113
	v_mov_b32_e32 v115, v109
	s_nop 0
	v_permlane16_swap_b32 v117, v117
	v_permlane16_swap_b32 v115, v115
	v_cmp_lt_i32_e64 s[4:5], 1, v233
	v_cmp_eq_u32_e64 s[6:7], 1, v233
	v_bfrev_b32_e32 v239, 1
	s_nop 0
	v_cndmask_b32_e64 v239, v239, 0, s[6:7]
	v_mul_f32_e32 v117, v141, v117
	v_xor_b32_e32 v117, v239, v117
	v_fma_f32 v116, v145, v113, v117
	v_cndmask_b32_e64 v113, v116, v113, s[4:5]
	v_mul_f32_e32 v115, v133, v115
	v_xor_b32_e32 v115, v239, v115
	v_fma_f32 v114, v137, v109, v115
	v_cndmask_b32_e64 v109, v114, v109, s[4:5]
.LBB0_387:
	s_waitcnt lgkmcnt(0)
	v_pk_mul_f32 v[114:115], v[110:111], s[36:37] op_sel_hi:[1,0]
	v_pk_mul_f32 v[118:119], v[106:107], s[36:37] op_sel_hi:[1,0]
	v_pk_mul_f32 v[116:117], v[112:113], s[36:37] op_sel_hi:[1,0]
	v_pk_mul_f32 v[120:121], v[108:109], s[36:37] op_sel_hi:[1,0]
	v_cndmask_b32_e64 v110, v110, v114, s[40:41]
	v_cndmask_b32_e64 v106, v106, v118, s[40:41]
	v_cndmask_b32_e64 v107, v107, v119, s[40:41]
	v_cndmask_b32_e64 v112, v112, v116, s[40:41]
	v_cndmask_b32_e64 v113, v113, v117, s[40:41]
	v_cndmask_b32_e64 v111, v111, v115, s[40:41]
	v_cndmask_b32_e64 v114, v108, v120, s[40:41]
	v_cndmask_b32_e64 v115, v109, v121, s[40:41]
	v_cvt_pk_bf16_f32 v108, v110, v111
	v_cvt_pk_bf16_f32 v109, v112, v113
	v_cvt_pk_bf16_f32 v110, v106, v107
	v_mov_b64_e32 v[106:107], s[62:63]
	s_movk_i32 s4, 0x1200
	v_mad_i64_i32 v[106:107], s[4:5], v210, s4, v[106:107]
	v_lshl_add_u64 v[112:113], v[0:1], 1, v[106:107]
	s_movk_i32 s4, 0xf000
	v_add_co_u32_e32 v112, vcc, s4, v112
	v_mov_b32_e32 v213, v212
	s_nop 0
	v_addc_co_u32_e32 v113, vcc, -1, v113, vcc
	v_cvt_pk_bf16_f32 v111, v114, v115
	flat_store_dwordx4 v[112:113], v[108:111] nt
	v_pk_mul_f32 v[102:103], v[102:103], v[212:213]
	s_and_b64 vcc, exec, s[46:47]
	v_mov_b32_e32 v108, v212
	v_mov_b32_e32 v109, v212
	v_pk_mul_f32 v[104:105], v[104:105], v[108:109]
	v_pk_mul_f32 v[100:101], v[100:101], v[108:109]
	v_pk_mul_f32 v[98:99], v[98:99], v[212:213]
	s_cbranch_vccnz .LBB0_413
	v_and_b32_e32 v109, 64, v226
	v_xor_b32_e32 v108, 16, v226
	v_add_u32_e32 v109, 64, v109
	v_cmp_lt_i32_e32 vcc, v108, v109
	s_nop 1
	v_cndmask_b32_e32 v108, v226, v108, vcc
	v_lshlrev_b32_e32 v112, 2, v108
	v_mov_b32_e32 v111, v102
	v_mov_b32_e32 v109, v98
	s_nop 0
	v_permlane16_swap_b32 v111, v111
	v_permlane16_swap_b32 v109, v109
	v_cmp_lt_i32_e64 s[4:5], 1, v233
	v_cmp_eq_u32_e64 s[6:7], 1, v233
	v_bfrev_b32_e32 v239, 1
	s_nop 0
	v_cndmask_b32_e64 v239, v239, 0, s[6:7]
	v_mul_f32_e32 v110, v102, v142
	v_mul_f32_e32 v111, v138, v111
	v_xor_b32_e32 v111, v239, v111
	v_add_f32_e32 v110, v110, v111
	v_cndmask_b32_e64 v102, v110, v102, s[4:5]
	v_mul_f32_e32 v108, v98, v134
	v_mul_f32_e32 v109, v130, v109
	v_xor_b32_e32 v109, v239, v109
	v_add_f32_e32 v108, v108, v109
	v_cndmask_b32_e64 v98, v108, v98, s[4:5]
	s_waitcnt lgkmcnt(0)
	v_mov_b32_e32 v111, v103
	v_mov_b32_e32 v109, v99
	s_nop 0
	v_permlane16_swap_b32 v111, v111
	v_permlane16_swap_b32 v109, v109
	v_cmp_lt_i32_e64 s[4:5], 1, v233
	v_cmp_eq_u32_e64 s[6:7], 1, v233
	v_bfrev_b32_e32 v239, 1
	s_nop 0
	v_cndmask_b32_e64 v239, v239, 0, s[6:7]
	v_mul_f32_e32 v108, v143, v103
	v_xor_b32_e32 v238, v239, v139
	v_fma_f32 v111, v238, v111, v108
	v_cndmask_b32_e64 v103, v111, v103, s[4:5]
	v_mul_f32_e32 v110, v135, v99
	v_xor_b32_e32 v238, v239, v131
	v_fma_f32 v109, v238, v109, v110
	v_cndmask_b32_e64 v99, v109, v99, s[4:5]
	s_waitcnt lgkmcnt(0)
	v_mov_b32_e32 v111, v104
	v_mov_b32_e32 v109, v100
	s_nop 0
	v_permlane16_swap_b32 v111, v111
	v_permlane16_swap_b32 v109, v109
	v_cmp_lt_i32_e64 s[4:5], 1, v233
	v_cmp_eq_u32_e64 s[6:7], 1, v233
	v_bfrev_b32_e32 v239, 1
	s_nop 0
	v_cndmask_b32_e64 v239, v239, 0, s[6:7]
	v_mul_f32_e32 v111, v140, v111
	v_xor_b32_e32 v111, v239, v111
	v_fma_f32 v110, v144, v104, v111
	v_cndmask_b32_e64 v104, v110, v104, s[4:5]
	v_mul_f32_e32 v109, v132, v109
	v_xor_b32_e32 v109, v239, v109
	v_fma_f32 v108, v136, v100, v109
	v_cndmask_b32_e64 v100, v108, v100, s[4:5]
	s_waitcnt lgkmcnt(0)
	v_mov_b32_e32 v111, v105
	v_mov_b32_e32 v109, v101
	s_nop 0
	v_permlane16_swap_b32 v111, v111
	v_permlane16_swap_b32 v109, v109
	v_cmp_lt_i32_e64 s[4:5], 1, v233
	v_cmp_eq_u32_e64 s[6:7], 1, v233
	v_bfrev_b32_e32 v239, 1
	s_nop 0
	v_cndmask_b32_e64 v239, v239, 0, s[6:7]
	v_mul_f32_e32 v111, v141, v111
	v_xor_b32_e32 v111, v239, v111
	v_fma_f32 v110, v145, v105, v111
	v_cndmask_b32_e64 v105, v110, v105, s[4:5]
	v_mul_f32_e32 v109, v133, v109
	v_xor_b32_e32 v109, v239, v109
	v_fma_f32 v108, v137, v101, v109
	v_cndmask_b32_e64 v101, v108, v101, s[4:5]

.LBB0_415:
	s_waitcnt vmcnt(0)
	v_pk_mul_f32 v[96:97], v[96:97], v[208:209] op_sel_hi:[1,0]
	v_pk_mul_f32 v[94:95], v[94:95], v[208:209] op_sel_hi:[1,0]
	v_pk_mul_f32 v[92:93], v[92:93], v[208:209] op_sel_hi:[1,0]
	s_and_b64 vcc, exec, s[42:43]
	v_pk_mul_f32 v[90:91], v[90:91], v[208:209] op_sel_hi:[1,0]
	s_cbranch_vccnz .LBB0_441
	v_and_b32_e32 v193, 64, v226
	v_xor_b32_e32 v177, 16, v226
	v_add_u32_e32 v193, 64, v193
	v_cmp_lt_i32_e32 vcc, v177, v193
	s_nop 1
	v_cndmask_b32_e32 v177, v226, v177, vcc
	v_lshlrev_b32_e32 v177, 2, v177
	v_mov_b32_e32 v213, v94
	v_mov_b32_e32 v211, v90
	s_nop 0
	v_permlane16_swap_b32 v213, v213
	v_permlane16_swap_b32 v211, v211
	v_cmp_lt_i32_e64 s[4:5], 1, v233
	v_cmp_eq_u32_e64 s[6:7], 1, v233
	v_bfrev_b32_e32 v239, 1
	s_nop 0
	v_cndmask_b32_e64 v239, v239, 0, s[6:7]
	v_mul_f32_e32 v212, v94, v126
	v_mul_f32_e32 v213, v122, v213
	v_xor_b32_e32 v213, v239, v213
	v_add_f32_e32 v212, v212, v213
	v_cndmask_b32_e64 v94, v212, v94, s[4:5]
	v_mul_f32_e32 v210, v90, v118
	v_mul_f32_e32 v211, v114, v211
	v_xor_b32_e32 v211, v239, v211
	v_add_f32_e32 v210, v210, v211
	v_cndmask_b32_e64 v90, v210, v90, s[4:5]
	s_waitcnt lgkmcnt(0)
	v_mov_b32_e32 v213, v95
	v_mov_b32_e32 v211, v91
	s_nop 0
	v_permlane16_swap_b32 v213, v213
	v_permlane16_swap_b32 v211, v211
	v_cmp_lt_i32_e64 s[4:5], 1, v233
	v_cmp_eq_u32_e64 s[6:7], 1, v233
	v_bfrev_b32_e32 v239, 1
	s_nop 0
	v_cndmask_b32_e64 v239, v239, 0, s[6:7]
	v_mul_f32_e32 v210, v127, v95
	v_xor_b32_e32 v238, v239, v123
	v_fma_f32 v213, v238, v213, v210
	v_cndmask_b32_e64 v95, v213, v95, s[4:5]
	v_mul_f32_e32 v212, v119, v91
	v_xor_b32_e32 v238, v239, v115
	v_fma_f32 v211, v238, v211, v212
	v_cndmask_b32_e64 v91, v211, v91, s[4:5]
	s_waitcnt lgkmcnt(0)
	v_mov_b32_e32 v213, v96
	v_mov_b32_e32 v211, v92
	s_nop 0
	v_permlane16_swap_b32 v213, v213
	v_permlane16_swap_b32 v211, v211
	v_cmp_lt_i32_e64 s[4:5], 1, v233
	v_cmp_eq_u32_e64 s[6:7], 1, v233
	v_bfrev_b32_e32 v239, 1
	s_nop 0
	v_cndmask_b32_e64 v239, v239, 0, s[6:7]
	v_mul_f32_e32 v213, v124, v213
	v_xor_b32_e32 v213, v239, v213
	v_fma_f32 v212, v128, v96, v213
	v_cndmask_b32_e64 v96, v212, v96, s[4:5]
	v_mul_f32_e32 v211, v116, v211
	v_xor_b32_e32 v211, v239, v211
	v_fma_f32 v210, v120, v92, v211
	v_cndmask_b32_e64 v92, v210, v92, s[4:5]
	s_waitcnt lgkmcnt(0)
	v_mov_b32_e32 v213, v97
	v_mov_b32_e32 v211, v93
	s_nop 0
	v_permlane16_swap_b32 v213, v213
	v_permlane16_swap_b32 v211, v211
	v_cmp_lt_i32_e64 s[4:5], 1, v233
	v_cmp_eq_u32_e64 s[6:7], 1, v233
	v_bfrev_b32_e32 v239, 1
	s_nop 0
	v_cndmask_b32_e64 v239, v239, 0, s[6:7]
	v_mul_f32_e32 v213, v125, v213
	v_xor_b32_e32 v213, v239, v213
	v_fma_f32 v212, v129, v97, v213
	v_cndmask_b32_e64 v97, v212, v97, s[4:5]
	v_mul_f32_e32 v211, v117, v211
	v_xor_b32_e32 v211, v239, v211
	v_fma_f32 v210, v121, v93, v211
	v_cndmask_b32_e64 v93, v210, v93, s[4:5]
.LBB0_441:
	s_waitcnt lgkmcnt(0)
	v_pk_mul_f32 v[210:211], v[94:95], s[36:37] op_sel_hi:[1,0]
	v_pk_mul_f32 v[216:217], v[90:91], s[36:37] op_sel_hi:[1,0]
	v_pk_mul_f32 v[212:213], v[96:97], s[36:37] op_sel_hi:[1,0]
	v_pk_mul_f32 v[218:219], v[92:93], s[36:37] op_sel_hi:[1,0]
	v_cndmask_b32_e64 v94, v94, v210, s[40:41]
	v_cndmask_b32_e64 v90, v90, v216, s[40:41]
	v_cndmask_b32_e64 v91, v91, v217, s[40:41]
	v_cndmask_b32_e64 v96, v96, v212, s[40:41]
	v_cndmask_b32_e64 v97, v97, v213, s[40:41]
	v_cndmask_b32_e64 v95, v95, v211, s[40:41]
	v_cndmask_b32_e64 v177, v92, v218, s[40:41]
	v_cndmask_b32_e64 v193, v93, v219, s[40:41]
	v_cvt_pk_bf16_f32 v92, v94, v95
	v_cvt_pk_bf16_f32 v93, v96, v97
	v_cvt_pk_bf16_f32 v94, v90, v91
	v_mov_b64_e32 v[90:91], s[62:63]
	s_movk_i32 s4, 0x1200
	v_mad_i64_i32 v[90:91], s[4:5], v206, s4, v[90:91]
	v_lshl_add_u64 v[96:97], v[0:1], 1, v[90:91]
	s_movk_i32 s4, 0xf000
	v_add_co_u32_e32 v96, vcc, s4, v96
	v_mov_b32_e32 v209, v208
	s_nop 0
	v_addc_co_u32_e32 v97, vcc, -1, v97, vcc
	v_cvt_pk_bf16_f32 v95, v177, v193
	flat_store_dwordx4 v[96:97], v[92:95] nt
	v_pk_mul_f32 v[86:87], v[86:87], v[208:209]
	s_and_b64 vcc, exec, s[46:47]
	v_mov_b32_e32 v92, v208
	v_mov_b32_e32 v93, v208
	v_pk_mul_f32 v[88:89], v[88:89], v[92:93]
	v_pk_mul_f32 v[84:85], v[84:85], v[92:93]
	v_pk_mul_f32 v[82:83], v[82:83], v[208:209]
	s_cbranch_vccnz .LBB0_467
	v_and_b32_e32 v93, 64, v226
	v_xor_b32_e32 v92, 16, v226
	v_add_u32_e32 v93, 64, v93
	v_cmp_lt_i32_e32 vcc, v92, v93
	s_nop 1
	v_cndmask_b32_e32 v92, v226, v92, vcc
	v_lshlrev_b32_e32 v96, 2, v92
	v_mov_b32_e32 v95, v86
	v_mov_b32_e32 v93, v82
	s_nop 0
	v_permlane16_swap_b32 v95, v95
	v_permlane16_swap_b32 v93, v93
	v_cmp_lt_i32_e64 s[4:5], 1, v233
	v_cmp_eq_u32_e64 s[6:7], 1, v233
	v_bfrev_b32_e32 v239, 1
	s_nop 0
	v_cndmask_b32_e64 v239, v239, 0, s[6:7]
	v_mul_f32_e32 v94, v86, v126
	v_mul_f32_e32 v95, v122, v95
	v_xor_b32_e32 v95, v239, v95
	v_add_f32_e32 v94, v94, v95
	v_cndmask_b32_e64 v86, v94, v86, s[4:5]
	v_mul_f32_e32 v92, v82, v118
	v_mul_f32_e32 v93, v114, v93
	v_xor_b32_e32 v93, v239, v93
	v_add_f32_e32 v92, v92, v93
	v_cndmask_b32_e64 v82, v92, v82, s[4:5]
	s_waitcnt lgkmcnt(0)
	v_mov_b32_e32 v95, v87
	v_mov_b32_e32 v93, v83
	s_nop 0
	v_permlane16_swap_b32 v95, v95
	v_permlane16_swap_b32 v93, v93
	v_cmp_lt_i32_e64 s[4:5], 1, v233
	v_cmp_eq_u32_e64 s[6:7], 1, v233
	v_bfrev_b32_e32 v239, 1
	s_nop 0
	v_cndmask_b32_e64 v239, v239, 0, s[6:7]
	v_mul_f32_e32 v92, v127, v87
	v_xor_b32_e32 v238, v239, v123
	v_fma_f32 v95, v238, v95, v92
	v_cndmask_b32_e64 v87, v95, v87, s[4:5]
	v_mul_f32_e32 v94, v119, v83
	v_xor_b32_e32 v238, v239, v115
	v_fma_f32 v93, v238, v93, v94
	v_cndmask_b32_e64 v83, v93, v83, s[4:5]
	s_waitcnt lgkmcnt(0)
	v_mov_b32_e32 v95, v88
	v_mov_b32_e32 v93, v84
	s_nop 0
	v_permlane16_swap_b32 v95, v95
	v_permlane16_swap_b32 v93, v93
	v_cmp_lt_i32_e64 s[4:5], 1, v233
	v_cmp_eq_u32_e64 s[6:7], 1, v233
	v_bfrev_b32_e32 v239, 1
	s_nop 0
	v_cndmask_b32_e64 v239, v239, 0, s[6:7]
	v_mul_f32_e32 v95, v124, v95
	v_xor_b32_e32 v95, v239, v95
	v_fma_f32 v94, v128, v88, v95
	v_cndmask_b32_e64 v88, v94, v88, s[4:5]
	v_mul_f32_e32 v93, v116, v93
	v_xor_b32_e32 v93, v239, v93
	v_fma_f32 v92, v120, v84, v93
	v_cndmask_b32_e64 v84, v92, v84, s[4:5]
	s_waitcnt lgkmcnt(0)
	v_mov_b32_e32 v95, v89
	v_mov_b32_e32 v93, v85
	s_nop 0
	v_permlane16_swap_b32 v95, v95
	v_permlane16_swap_b32 v93, v93
	v_cmp_lt_i32_e64 s[4:5], 1, v233
	v_cmp_eq_u32_e64 s[6:7], 1, v233
	v_bfrev_b32_e32 v239, 1
	s_nop 0
	v_cndmask_b32_e64 v239, v239, 0, s[6:7]
	v_mul_f32_e32 v95, v125, v95
	v_xor_b32_e32 v95, v239, v95
	v_fma_f32 v94, v129, v89, v95
	v_cndmask_b32_e64 v89, v94, v89, s[4:5]
	v_mul_f32_e32 v93, v117, v93
	v_xor_b32_e32 v93, v239, v93
	v_fma_f32 v92, v121, v85, v93
	v_cndmask_b32_e64 v85, v92, v85, s[4:5]
.LBB0_467:
	s_waitcnt lgkmcnt(0)
	v_pk_mul_f32 v[92:93], v[86:87], s[36:37] op_sel_hi:[1,0]
	v_pk_mul_f32 v[96:97], v[82:83], s[36:37] op_sel_hi:[1,0]
	v_pk_mul_f32 v[206:207], v[84:85], s[36:37] op_sel_hi:[1,0]
	v_cndmask_b32_e64 v86, v86, v92, s[44:45]
	v_cndmask_b32_e64 v87, v87, v93, s[44:45]
	v_cndmask_b32_e64 v92, v84, v206, s[44:45]
	v_cndmask_b32_e64 v84, v82, v96, s[44:45]
	v_cvt_pk_bf16_f32 v82, v86, v87
	v_lshl_add_u64 v[86:87], v[214:215], 1, v[90:91]
	s_movk_i32 s4, 0xf100
	v_add_co_u32_e32 v86, vcc, s4, v86
	v_pk_mul_f32 v[94:95], v[88:89], s[36:37] op_sel_hi:[1,0]
	s_nop 0
	v_addc_co_u32_e32 v87, vcc, -1, v87, vcc
	v_cndmask_b32_e64 v85, v85, v207, s[44:45]
	v_pk_mul_f32 v[80:81], v[80:81], v[204:205] op_sel_hi:[1,0]
	v_pk_mul_f32 v[78:79], v[78:79], v[204:205] op_sel_hi:[1,0]
	v_pk_mul_f32 v[76:77], v[76:77], v[204:205] op_sel_hi:[1,0]
	s_and_b64 vcc, exec, s[42:43]
	v_pk_mul_f32 v[74:75], v[74:75], v[204:205] op_sel_hi:[1,0]
	v_cndmask_b32_e64 v88, v88, v94, s[44:45]
	v_cndmask_b32_e64 v89, v89, v95, s[44:45]
	v_cndmask_b32_e64 v93, v83, v97, s[44:45]
	v_cvt_pk_bf16_f32 v83, v88, v89
	v_cvt_pk_bf16_f32 v84, v84, v93
	v_cvt_pk_bf16_f32 v85, v92, v85
	flat_store_dwordx4 v[86:87], v[82:85] nt
	s_cbranch_vccnz .LBB0_493
	s_nop 0
	v_and_b32_e32 v83, 64, v226
	v_xor_b32_e32 v82, 16, v226
	v_add_u32_e32 v83, 64, v83
	v_cmp_lt_i32_e32 vcc, v82, v83
	s_nop 1
	v_cndmask_b32_e32 v82, v226, v82, vcc
	v_lshlrev_b32_e32 v86, 2, v82
	v_mov_b32_e32 v85, v78
	v_mov_b32_e32 v83, v74
	s_nop 0
	v_permlane16_swap_b32 v85, v85
	v_permlane16_swap_b32 v83, v83
	v_cmp_lt_i32_e64 s[4:5], 1, v233
	v_cmp_eq_u32_e64 s[6:7], 1, v233
	v_bfrev_b32_e32 v239, 1
	s_nop 0
	v_cndmask_b32_e64 v239, v239, 0, s[6:7]
	v_mul_f32_e32 v84, v78, v110
	v_mul_f32_e32 v85, v106, v85
	v_xor_b32_e32 v85, v239, v85
	v_add_f32_e32 v84, v84, v85
	v_cndmask_b32_e64 v78, v84, v78, s[4:5]
	v_mul_f32_e32 v82, v74, v102
	v_mul_f32_e32 v83, v98, v83
	v_xor_b32_e32 v83, v239, v83
	v_add_f32_e32 v82, v82, v83
	v_cndmask_b32_e64 v74, v82, v74, s[4:5]
	s_waitcnt lgkmcnt(0)
	v_mov_b32_e32 v85, v79
	v_mov_b32_e32 v83, v75
	s_nop 0
	v_permlane16_swap_b32 v85, v85
	v_permlane16_swap_b32 v83, v83
	v_cmp_lt_i32_e64 s[4:5], 1, v233
	v_cmp_eq_u32_e64 s[6:7], 1, v233
	v_bfrev_b32_e32 v239, 1
	s_nop 0
	v_cndmask_b32_e64 v239, v239, 0, s[6:7]
	v_mul_f32_e32 v82, v111, v79
	v_xor_b32_e32 v238, v239, v107
	v_fma_f32 v85, v238, v85, v82
	v_cndmask_b32_e64 v79, v85, v79, s[4:5]
	v_mul_f32_e32 v84, v103, v75
	v_xor_b32_e32 v238, v239, v99
	v_fma_f32 v83, v238, v83, v84
	v_cndmask_b32_e64 v75, v83, v75, s[4:5]
	s_waitcnt lgkmcnt(0)
	v_mov_b32_e32 v85, v80
	v_mov_b32_e32 v83, v76
	s_nop 0
	v_permlane16_swap_b32 v85, v85
	v_permlane16_swap_b32 v83, v83
	v_cmp_lt_i32_e64 s[4:5], 1, v233
	v_cmp_eq_u32_e64 s[6:7], 1, v233
	v_bfrev_b32_e32 v239, 1
	s_nop 0
	v_cndmask_b32_e64 v239, v239, 0, s[6:7]
	v_mul_f32_e32 v85, v108, v85
	v_xor_b32_e32 v85, v239, v85
	v_fma_f32 v84, v112, v80, v85
	v_cndmask_b32_e64 v80, v84, v80, s[4:5]
	v_mul_f32_e32 v83, v100, v83
	v_xor_b32_e32 v83, v239, v83
	v_fma_f32 v82, v104, v76, v83
	v_cndmask_b32_e64 v76, v82, v76, s[4:5]
	s_waitcnt lgkmcnt(0)
	v_mov_b32_e32 v85, v81
	v_mov_b32_e32 v83, v77
	s_nop 0
	v_permlane16_swap_b32 v85, v85
	v_permlane16_swap_b32 v83, v83
	v_cmp_lt_i32_e64 s[4:5], 1, v233
	v_cmp_eq_u32_e64 s[6:7], 1, v233
	v_bfrev_b32_e32 v239, 1
	s_nop 0
	v_cndmask_b32_e64 v239, v239, 0, s[6:7]
	v_mul_f32_e32 v85, v109, v85
	v_xor_b32_e32 v85, v239, v85
	v_fma_f32 v84, v113, v81, v85
	v_cndmask_b32_e64 v81, v84, v81, s[4:5]
	v_mul_f32_e32 v83, v101, v83
	v_xor_b32_e32 v83, v239, v83
	v_fma_f32 v82, v105, v77, v83
	v_cndmask_b32_e64 v77, v82, v77, s[4:5]
.LBB0_493:
	s_waitcnt lgkmcnt(0)
	v_pk_mul_f32 v[82:83], v[78:79], s[36:37] op_sel_hi:[1,0]
	v_pk_mul_f32 v[86:87], v[74:75], s[36:37] op_sel_hi:[1,0]
	v_pk_mul_f32 v[84:85], v[80:81], s[36:37] op_sel_hi:[1,0]
	v_pk_mul_f32 v[88:89], v[76:77], s[36:37] op_sel_hi:[1,0]
	v_cndmask_b32_e64 v78, v78, v82, s[40:41]
	v_cndmask_b32_e64 v74, v74, v86, s[40:41]
	v_cndmask_b32_e64 v75, v75, v87, s[40:41]
	v_cndmask_b32_e64 v80, v80, v84, s[40:41]
	v_cndmask_b32_e64 v81, v81, v85, s[40:41]
	v_cndmask_b32_e64 v79, v79, v83, s[40:41]
	v_cndmask_b32_e64 v82, v76, v88, s[40:41]
	v_cndmask_b32_e64 v83, v77, v89, s[40:41]
	v_cvt_pk_bf16_f32 v76, v78, v79
	v_cvt_pk_bf16_f32 v77, v80, v81
	v_cvt_pk_bf16_f32 v78, v74, v75
	v_mov_b64_e32 v[74:75], s[62:63]
	s_movk_i32 s4, 0x1200
	v_mad_i64_i32 v[74:75], s[4:5], v202, s4, v[74:75]
	v_lshl_add_u64 v[80:81], v[0:1], 1, v[74:75]
	s_movk_i32 s4, 0xf000
	v_add_co_u32_e32 v80, vcc, s4, v80
	v_mov_b32_e32 v205, v204
	s_nop 0
	v_addc_co_u32_e32 v81, vcc, -1, v81, vcc
	v_cvt_pk_bf16_f32 v79, v82, v83
	flat_store_dwordx4 v[80:81], v[76:79] nt
	v_pk_mul_f32 v[70:71], v[70:71], v[204:205]
	s_and_b64 vcc, exec, s[46:47]
	v_mov_b32_e32 v76, v204
	v_mov_b32_e32 v77, v204
	v_pk_mul_f32 v[72:73], v[72:73], v[76:77]
	v_pk_mul_f32 v[68:69], v[68:69], v[76:77]
	v_pk_mul_f32 v[66:67], v[66:67], v[204:205]
	s_cbranch_vccnz .LBB0_519
	v_and_b32_e32 v77, 64, v226
	v_xor_b32_e32 v76, 16, v226
	v_add_u32_e32 v77, 64, v77
	v_cmp_lt_i32_e32 vcc, v76, v77
	s_nop 1
	v_cndmask_b32_e32 v76, v226, v76, vcc
	v_lshlrev_b32_e32 v80, 2, v76
	v_mov_b32_e32 v79, v70
	v_mov_b32_e32 v77, v66
	s_nop 0
	v_permlane16_swap_b32 v79, v79
	v_permlane16_swap_b32 v77, v77
	v_cmp_lt_i32_e64 s[4:5], 1, v233
	v_cmp_eq_u32_e64 s[6:7], 1, v233
	v_bfrev_b32_e32 v239, 1
	s_nop 0
	v_cndmask_b32_e64 v239, v239, 0, s[6:7]
	v_mul_f32_e32 v78, v70, v110
	v_mul_f32_e32 v79, v106, v79
	v_xor_b32_e32 v79, v239, v79
	v_add_f32_e32 v78, v78, v79
	v_cndmask_b32_e64 v70, v78, v70, s[4:5]
	v_mul_f32_e32 v76, v66, v102
	v_mul_f32_e32 v77, v98, v77
	v_xor_b32_e32 v77, v239, v77
	v_add_f32_e32 v76, v76, v77
	v_cndmask_b32_e64 v66, v76, v66, s[4:5]
	s_waitcnt lgkmcnt(0)
	v_mov_b32_e32 v79, v71
	v_mov_b32_e32 v77, v67
	s_nop 0
	v_permlane16_swap_b32 v79, v79
	v_permlane16_swap_b32 v77, v77
	v_cmp_lt_i32_e64 s[4:5], 1, v233
	v_cmp_eq_u32_e64 s[6:7], 1, v233
	v_bfrev_b32_e32 v239, 1
	s_nop 0
	v_cndmask_b32_e64 v239, v239, 0, s[6:7]
	v_mul_f32_e32 v76, v111, v71
	v_xor_b32_e32 v238, v239, v107
	v_fma_f32 v79, v238, v79, v76
	v_cndmask_b32_e64 v71, v79, v71, s[4:5]
	v_mul_f32_e32 v78, v103, v67
	v_xor_b32_e32 v238, v239, v99
	v_fma_f32 v77, v238, v77, v78
	v_cndmask_b32_e64 v67, v77, v67, s[4:5]
	s_waitcnt lgkmcnt(0)
	v_mov_b32_e32 v79, v72
	v_mov_b32_e32 v77, v68
	s_nop 0
	v_permlane16_swap_b32 v79, v79
	v_permlane16_swap_b32 v77, v77
	v_cmp_lt_i32_e64 s[4:5], 1, v233
	v_cmp_eq_u32_e64 s[6:7], 1, v233
	v_bfrev_b32_e32 v239, 1
	s_nop 0
	v_cndmask_b32_e64 v239, v239, 0, s[6:7]
	v_mul_f32_e32 v79, v108, v79
	v_xor_b32_e32 v79, v239, v79
	v_fma_f32 v78, v112, v72, v79
	v_cndmask_b32_e64 v72, v78, v72, s[4:5]
	v_mul_f32_e32 v77, v100, v77
	v_xor_b32_e32 v77, v239, v77
	v_fma_f32 v76, v104, v68, v77
	v_cndmask_b32_e64 v68, v76, v68, s[4:5]
	s_waitcnt lgkmcnt(0)
	v_mov_b32_e32 v79, v73
	v_mov_b32_e32 v77, v69
	s_nop 0
	v_permlane16_swap_b32 v79, v79
	v_permlane16_swap_b32 v77, v77
	v_cmp_lt_i32_e64 s[4:5], 1, v233
	v_cmp_eq_u32_e64 s[6:7], 1, v233
	v_bfrev_b32_e32 v239, 1
	s_nop 0
	v_cndmask_b32_e64 v239, v239, 0, s[6:7]
	v_mul_f32_e32 v79, v109, v79
	v_xor_b32_e32 v79, v239, v79
	v_fma_f32 v78, v113, v73, v79
	v_cndmask_b32_e64 v73, v78, v73, s[4:5]
	v_mul_f32_e32 v77, v101, v77
	v_xor_b32_e32 v77, v239, v77
	v_fma_f32 v76, v105, v69, v77
	v_cndmask_b32_e64 v69, v76, v69, s[4:5]

.LBB0_521:
	s_waitcnt vmcnt(0)
	v_pk_mul_f32 v[64:65], v[64:65], v[200:201] op_sel_hi:[1,0]
	v_pk_mul_f32 v[62:63], v[62:63], v[200:201] op_sel_hi:[1,0]
	v_pk_mul_f32 v[60:61], v[60:61], v[200:201] op_sel_hi:[1,0]
	s_and_b64 vcc, exec, s[42:43]
	v_pk_mul_f32 v[58:59], v[58:59], v[200:201] op_sel_hi:[1,0]
	s_cbranch_vccnz .LBB0_547
	v_and_b32_e32 v67, 64, v226
	v_xor_b32_e32 v66, 16, v226
	v_add_u32_e32 v67, 64, v67
	v_cmp_lt_i32_e32 vcc, v66, v67
	s_nop 1
	v_cndmask_b32_e32 v66, v226, v66, vcc
	v_lshlrev_b32_e32 v70, 2, v66
	v_mov_b32_e32 v69, v62
	v_mov_b32_e32 v67, v58
	s_nop 0
	v_permlane16_swap_b32 v69, v69
	v_permlane16_swap_b32 v67, v67
	v_cmp_lt_i32_e64 s[4:5], 1, v233
	v_cmp_eq_u32_e64 s[6:7], 1, v233
	v_bfrev_b32_e32 v239, 1
	s_nop 0
	v_cndmask_b32_e64 v239, v239, 0, s[6:7]
	v_mul_f32_e32 v68, v62, v158
	v_mul_f32_e32 v69, v154, v69
	v_xor_b32_e32 v69, v239, v69
	v_add_f32_e32 v68, v68, v69
	v_cndmask_b32_e64 v62, v68, v62, s[4:5]
	v_mul_f32_e32 v66, v58, v150
	v_mul_f32_e32 v67, v146, v67
	v_xor_b32_e32 v67, v239, v67
	v_add_f32_e32 v66, v66, v67
	v_cndmask_b32_e64 v58, v66, v58, s[4:5]
	s_waitcnt lgkmcnt(0)
	v_mov_b32_e32 v69, v63
	v_mov_b32_e32 v67, v59
	s_nop 0
	v_permlane16_swap_b32 v69, v69
	v_permlane16_swap_b32 v67, v67
	v_cmp_lt_i32_e64 s[4:5], 1, v233
	v_cmp_eq_u32_e64 s[6:7], 1, v233
	v_bfrev_b32_e32 v239, 1
	s_nop 0
	v_cndmask_b32_e64 v239, v239, 0, s[6:7]
	v_mul_f32_e32 v66, v159, v63
	v_xor_b32_e32 v238, v239, v155
	v_fma_f32 v69, v238, v69, v66
	v_cndmask_b32_e64 v63, v69, v63, s[4:5]
	v_mul_f32_e32 v68, v151, v59
	v_xor_b32_e32 v238, v239, v147
	v_fma_f32 v67, v238, v67, v68
	v_cndmask_b32_e64 v59, v67, v59, s[4:5]
	s_waitcnt lgkmcnt(0)
	v_mov_b32_e32 v69, v64
	v_mov_b32_e32 v67, v60
	s_nop 0
	v_permlane16_swap_b32 v69, v69
	v_permlane16_swap_b32 v67, v67
	v_cmp_lt_i32_e64 s[4:5], 1, v233
	v_cmp_eq_u32_e64 s[6:7], 1, v233
	v_bfrev_b32_e32 v239, 1
	s_nop 0
	v_cndmask_b32_e64 v239, v239, 0, s[6:7]
	v_mul_f32_e32 v69, v156, v69
	v_xor_b32_e32 v69, v239, v69
	v_fma_f32 v68, v160, v64, v69
	v_cndmask_b32_e64 v64, v68, v64, s[4:5]
	v_mul_f32_e32 v67, v148, v67
	v_xor_b32_e32 v67, v239, v67
	v_fma_f32 v66, v152, v60, v67
	v_cndmask_b32_e64 v60, v66, v60, s[4:5]
	s_waitcnt lgkmcnt(0)
	v_mov_b32_e32 v69, v65
	v_mov_b32_e32 v67, v61
	s_nop 0
	v_permlane16_swap_b32 v69, v69
	v_permlane16_swap_b32 v67, v67
	v_cmp_lt_i32_e64 s[4:5], 1, v233
	v_cmp_eq_u32_e64 s[6:7], 1, v233
	v_bfrev_b32_e32 v239, 1
	s_nop 0
	v_cndmask_b32_e64 v239, v239, 0, s[6:7]
	v_mul_f32_e32 v69, v157, v69
	v_xor_b32_e32 v69, v239, v69
	v_fma_f32 v68, v161, v65, v69
	v_cndmask_b32_e64 v65, v68, v65, s[4:5]
	v_mul_f32_e32 v67, v149, v67
	v_xor_b32_e32 v67, v239, v67
	v_fma_f32 v66, v153, v61, v67
	v_cndmask_b32_e64 v61, v66, v61, s[4:5]
.LBB0_547:
	s_waitcnt lgkmcnt(0)
	v_pk_mul_f32 v[66:67], v[62:63], s[36:37] op_sel_hi:[1,0]
	v_pk_mul_f32 v[70:71], v[58:59], s[36:37] op_sel_hi:[1,0]
	v_pk_mul_f32 v[68:69], v[64:65], s[36:37] op_sel_hi:[1,0]
	v_pk_mul_f32 v[72:73], v[60:61], s[36:37] op_sel_hi:[1,0]
	v_cndmask_b32_e64 v62, v62, v66, s[40:41]
	v_cndmask_b32_e64 v58, v58, v70, s[40:41]
	v_cndmask_b32_e64 v59, v59, v71, s[40:41]
	v_cndmask_b32_e64 v64, v64, v68, s[40:41]
	v_cndmask_b32_e64 v65, v65, v69, s[40:41]
	v_cndmask_b32_e64 v63, v63, v67, s[40:41]
	v_cndmask_b32_e64 v66, v60, v72, s[40:41]
	v_cndmask_b32_e64 v67, v61, v73, s[40:41]
	v_cvt_pk_bf16_f32 v60, v62, v63
	v_cvt_pk_bf16_f32 v61, v64, v65
	v_cvt_pk_bf16_f32 v62, v58, v59
	v_mov_b64_e32 v[58:59], s[62:63]
	s_movk_i32 s4, 0x1200
	v_mad_i64_i32 v[58:59], s[4:5], v198, s4, v[58:59]
	v_lshl_add_u64 v[64:65], v[0:1], 1, v[58:59]
	s_movk_i32 s4, 0xf000
	v_add_co_u32_e32 v64, vcc, s4, v64
	v_mov_b32_e32 v201, v200
	s_nop 0
	v_addc_co_u32_e32 v65, vcc, -1, v65, vcc
	v_cvt_pk_bf16_f32 v63, v66, v67
	flat_store_dwordx4 v[64:65], v[60:63] nt
	v_pk_mul_f32 v[54:55], v[54:55], v[200:201]
	s_and_b64 vcc, exec, s[46:47]
	v_mov_b32_e32 v60, v200
	v_mov_b32_e32 v61, v200
	v_pk_mul_f32 v[56:57], v[56:57], v[60:61]
	v_pk_mul_f32 v[52:53], v[52:53], v[60:61]
	v_pk_mul_f32 v[50:51], v[50:51], v[200:201]
	s_cbranch_vccnz .LBB0_573
	v_and_b32_e32 v61, 64, v226
	v_xor_b32_e32 v60, 16, v226
	v_add_u32_e32 v61, 64, v61
	v_cmp_lt_i32_e32 vcc, v60, v61
	s_nop 1
	v_cndmask_b32_e32 v60, v226, v60, vcc
	v_lshlrev_b32_e32 v64, 2, v60
	v_mov_b32_e32 v63, v54
	v_mov_b32_e32 v61, v50
	s_nop 0
	v_permlane16_swap_b32 v63, v63
	v_permlane16_swap_b32 v61, v61
	v_cmp_lt_i32_e64 s[4:5], 1, v233
	v_cmp_eq_u32_e64 s[6:7], 1, v233
	v_bfrev_b32_e32 v239, 1
	s_nop 0
	v_cndmask_b32_e64 v239, v239, 0, s[6:7]
	v_mul_f32_e32 v62, v54, v158
	v_mul_f32_e32 v63, v154, v63
	v_xor_b32_e32 v63, v239, v63
	v_add_f32_e32 v62, v62, v63
	v_cndmask_b32_e64 v54, v62, v54, s[4:5]
	v_mul_f32_e32 v60, v50, v150
	v_mul_f32_e32 v61, v146, v61
	v_xor_b32_e32 v61, v239, v61
	v_add_f32_e32 v60, v60, v61
	v_cndmask_b32_e64 v50, v60, v50, s[4:5]
	s_waitcnt lgkmcnt(0)
	v_mov_b32_e32 v63, v55
	v_mov_b32_e32 v61, v51
	s_nop 0
	v_permlane16_swap_b32 v63, v63
	v_permlane16_swap_b32 v61, v61
	v_cmp_lt_i32_e64 s[4:5], 1, v233
	v_cmp_eq_u32_e64 s[6:7], 1, v233
	v_bfrev_b32_e32 v239, 1
	s_nop 0
	v_cndmask_b32_e64 v239, v239, 0, s[6:7]
	v_mul_f32_e32 v60, v159, v55
	v_xor_b32_e32 v238, v239, v155
	v_fma_f32 v63, v238, v63, v60
	v_cndmask_b32_e64 v55, v63, v55, s[4:5]
	v_mul_f32_e32 v62, v151, v51
	v_xor_b32_e32 v238, v239, v147
	v_fma_f32 v61, v238, v61, v62
	v_cndmask_b32_e64 v51, v61, v51, s[4:5]
	s_waitcnt lgkmcnt(0)
	v_mov_b32_e32 v63, v56
	v_mov_b32_e32 v61, v52
	s_nop 0
	v_permlane16_swap_b32 v63, v63
	v_permlane16_swap_b32 v61, v61
	v_cmp_lt_i32_e64 s[4:5], 1, v233
	v_cmp_eq_u32_e64 s[6:7], 1, v233
	v_bfrev_b32_e32 v239, 1
	s_nop 0
	v_cndmask_b32_e64 v239, v239, 0, s[6:7]
	v_mul_f32_e32 v63, v156, v63
	v_xor_b32_e32 v63, v239, v63
	v_fma_f32 v62, v160, v56, v63
	v_cndmask_b32_e64 v56, v62, v56, s[4:5]
	v_mul_f32_e32 v61, v148, v61
	v_xor_b32_e32 v61, v239, v61
	v_fma_f32 v60, v152, v52, v61
	v_cndmask_b32_e64 v52, v60, v52, s[4:5]
	s_waitcnt lgkmcnt(0)
	v_mov_b32_e32 v63, v57
	v_mov_b32_e32 v61, v53
	s_nop 0
	v_permlane16_swap_b32 v63, v63
	v_permlane16_swap_b32 v61, v61
	v_cmp_lt_i32_e64 s[4:5], 1, v233
	v_cmp_eq_u32_e64 s[6:7], 1, v233
	v_bfrev_b32_e32 v239, 1
	s_nop 0
	v_cndmask_b32_e64 v239, v239, 0, s[6:7]
	v_mul_f32_e32 v63, v157, v63
	v_xor_b32_e32 v63, v239, v63
	v_fma_f32 v62, v161, v57, v63
	v_cndmask_b32_e64 v57, v62, v57, s[4:5]
	v_mul_f32_e32 v61, v149, v61
	v_xor_b32_e32 v61, v239, v61
	v_fma_f32 v60, v153, v53, v61
	v_cndmask_b32_e64 v53, v60, v53, s[4:5]
.LBB0_573:
	s_waitcnt lgkmcnt(0)
	v_pk_mul_f32 v[60:61], v[54:55], s[36:37] op_sel_hi:[1,0]
	v_pk_mul_f32 v[64:65], v[50:51], s[36:37] op_sel_hi:[1,0]
	v_pk_mul_f32 v[66:67], v[52:53], s[36:37] op_sel_hi:[1,0]
	v_cndmask_b32_e64 v54, v54, v60, s[44:45]
	v_cndmask_b32_e64 v55, v55, v61, s[44:45]
	v_cndmask_b32_e64 v60, v52, v66, s[44:45]
	v_cndmask_b32_e64 v52, v50, v64, s[44:45]
	v_cvt_pk_bf16_f32 v50, v54, v55
	v_lshl_add_u64 v[54:55], v[214:215], 1, v[58:59]
	s_movk_i32 s4, 0xf100
	v_add_co_u32_e32 v54, vcc, s4, v54
	v_pk_mul_f32 v[62:63], v[56:57], s[36:37] op_sel_hi:[1,0]
	s_nop 0
	v_addc_co_u32_e32 v55, vcc, -1, v55, vcc
	v_cndmask_b32_e64 v53, v53, v67, s[44:45]
	v_pk_mul_f32 v[48:49], v[48:49], v[196:197] op_sel_hi:[1,0]
	v_pk_mul_f32 v[46:47], v[46:47], v[196:197] op_sel_hi:[1,0]
	v_pk_mul_f32 v[44:45], v[44:45], v[196:197] op_sel_hi:[1,0]
	s_and_b64 vcc, exec, s[42:43]
	v_pk_mul_f32 v[42:43], v[42:43], v[196:197] op_sel_hi:[1,0]
	v_cndmask_b32_e64 v56, v56, v62, s[44:45]
	v_cndmask_b32_e64 v57, v57, v63, s[44:45]
	v_cndmask_b32_e64 v61, v51, v65, s[44:45]
	v_cvt_pk_bf16_f32 v51, v56, v57
	v_cvt_pk_bf16_f32 v52, v52, v61
	v_cvt_pk_bf16_f32 v53, v60, v53
	flat_store_dwordx4 v[54:55], v[50:53] nt
	s_cbranch_vccnz .LBB0_599
	s_nop 0
	v_and_b32_e32 v51, 64, v226
	v_xor_b32_e32 v50, 16, v226
	v_add_u32_e32 v51, 64, v51
	v_cmp_lt_i32_e32 vcc, v50, v51
	s_nop 1
	v_cndmask_b32_e32 v50, v226, v50, vcc
	v_lshlrev_b32_e32 v54, 2, v50
	v_mov_b32_e32 v53, v46
	v_mov_b32_e32 v51, v42
	s_nop 0
	v_permlane16_swap_b32 v53, v53
	v_permlane16_swap_b32 v51, v51
	v_cmp_lt_i32_e64 s[4:5], 1, v233
	v_cmp_eq_u32_e64 s[6:7], 1, v233
	v_bfrev_b32_e32 v239, 1
	s_nop 0
	v_cndmask_b32_e64 v239, v239, 0, s[6:7]
	v_mul_f32_e32 v52, v46, v142
	v_mul_f32_e32 v53, v138, v53
	v_xor_b32_e32 v53, v239, v53
	v_add_f32_e32 v52, v52, v53
	v_cndmask_b32_e64 v46, v52, v46, s[4:5]
	v_mul_f32_e32 v50, v42, v134
	v_mul_f32_e32 v51, v130, v51
	v_xor_b32_e32 v51, v239, v51
	v_add_f32_e32 v50, v50, v51
	v_cndmask_b32_e64 v42, v50, v42, s[4:5]
	s_waitcnt lgkmcnt(0)
	v_mov_b32_e32 v53, v47
	v_mov_b32_e32 v51, v43
	s_nop 0
	v_permlane16_swap_b32 v53, v53
	v_permlane16_swap_b32 v51, v51
	v_cmp_lt_i32_e64 s[4:5], 1, v233
	v_cmp_eq_u32_e64 s[6:7], 1, v233
	v_bfrev_b32_e32 v239, 1
	s_nop 0
	v_cndmask_b32_e64 v239, v239, 0, s[6:7]
	v_mul_f32_e32 v50, v143, v47
	v_xor_b32_e32 v238, v239, v139
	v_fma_f32 v53, v238, v53, v50
	v_cndmask_b32_e64 v47, v53, v47, s[4:5]
	v_mul_f32_e32 v52, v135, v43
	v_xor_b32_e32 v238, v239, v131
	v_fma_f32 v51, v238, v51, v52
	v_cndmask_b32_e64 v43, v51, v43, s[4:5]
	s_waitcnt lgkmcnt(0)
	v_mov_b32_e32 v53, v48
	v_mov_b32_e32 v51, v44
	s_nop 0
	v_permlane16_swap_b32 v53, v53
	v_permlane16_swap_b32 v51, v51
	v_cmp_lt_i32_e64 s[4:5], 1, v233
	v_cmp_eq_u32_e64 s[6:7], 1, v233
	v_bfrev_b32_e32 v239, 1
	s_nop 0
	v_cndmask_b32_e64 v239, v239, 0, s[6:7]
	v_mul_f32_e32 v53, v140, v53
	v_xor_b32_e32 v53, v239, v53
	v_fma_f32 v52, v144, v48, v53
	v_cndmask_b32_e64 v48, v52, v48, s[4:5]
	v_mul_f32_e32 v51, v132, v51
	v_xor_b32_e32 v51, v239, v51
	v_fma_f32 v50, v136, v44, v51
	v_cndmask_b32_e64 v44, v50, v44, s[4:5]
	s_waitcnt lgkmcnt(0)
	v_mov_b32_e32 v53, v49
	v_mov_b32_e32 v51, v45
	s_nop 0
	v_permlane16_swap_b32 v53, v53
	v_permlane16_swap_b32 v51, v51
	v_cmp_lt_i32_e64 s[4:5], 1, v233
	v_cmp_eq_u32_e64 s[6:7], 1, v233
	v_bfrev_b32_e32 v239, 1
	s_nop 0
	v_cndmask_b32_e64 v239, v239, 0, s[6:7]
	v_mul_f32_e32 v53, v141, v53
	v_xor_b32_e32 v53, v239, v53
	v_fma_f32 v52, v145, v49, v53
	v_cndmask_b32_e64 v49, v52, v49, s[4:5]
	v_mul_f32_e32 v51, v133, v51
	v_xor_b32_e32 v51, v239, v51
	v_fma_f32 v50, v137, v45, v51
	v_cndmask_b32_e64 v45, v50, v45, s[4:5]
.LBB0_599:
	s_waitcnt lgkmcnt(0)
	v_pk_mul_f32 v[50:51], v[46:47], s[36:37] op_sel_hi:[1,0]
	v_pk_mul_f32 v[54:55], v[42:43], s[36:37] op_sel_hi:[1,0]
	v_pk_mul_f32 v[52:53], v[48:49], s[36:37] op_sel_hi:[1,0]
	v_pk_mul_f32 v[56:57], v[44:45], s[36:37] op_sel_hi:[1,0]
	v_cndmask_b32_e64 v46, v46, v50, s[40:41]
	v_cndmask_b32_e64 v42, v42, v54, s[40:41]
	v_cndmask_b32_e64 v43, v43, v55, s[40:41]
	v_cndmask_b32_e64 v48, v48, v52, s[40:41]
	v_cndmask_b32_e64 v49, v49, v53, s[40:41]
	v_cndmask_b32_e64 v47, v47, v51, s[40:41]
	v_cndmask_b32_e64 v50, v44, v56, s[40:41]
	v_cndmask_b32_e64 v51, v45, v57, s[40:41]
	v_cvt_pk_bf16_f32 v44, v46, v47
	v_cvt_pk_bf16_f32 v45, v48, v49
	v_cvt_pk_bf16_f32 v46, v42, v43
	v_mov_b64_e32 v[42:43], s[62:63]
	s_movk_i32 s4, 0x1200
	v_mad_i64_i32 v[42:43], s[4:5], v194, s4, v[42:43]
	v_lshl_add_u64 v[48:49], v[0:1], 1, v[42:43]
	s_movk_i32 s4, 0xf000
	v_add_co_u32_e32 v48, vcc, s4, v48
	v_mov_b32_e32 v197, v196
	s_nop 0
	v_addc_co_u32_e32 v49, vcc, -1, v49, vcc
	v_cvt_pk_bf16_f32 v47, v50, v51
	flat_store_dwordx4 v[48:49], v[44:47] nt
	v_pk_mul_f32 v[38:39], v[38:39], v[196:197]
	s_and_b64 vcc, exec, s[46:47]
	v_mov_b32_e32 v44, v196
	v_mov_b32_e32 v45, v196
	v_pk_mul_f32 v[40:41], v[40:41], v[44:45]
	v_pk_mul_f32 v[36:37], v[36:37], v[44:45]
	v_pk_mul_f32 v[34:35], v[34:35], v[196:197]
	s_cbranch_vccnz .LBB0_625
	v_and_b32_e32 v45, 64, v226
	v_xor_b32_e32 v44, 16, v226
	v_add_u32_e32 v45, 64, v45
	v_cmp_lt_i32_e32 vcc, v44, v45
	s_nop 1
	v_cndmask_b32_e32 v44, v226, v44, vcc
	v_lshlrev_b32_e32 v48, 2, v44
	v_mov_b32_e32 v47, v38
	v_mov_b32_e32 v45, v34
	s_nop 0
	v_permlane16_swap_b32 v47, v47
	v_permlane16_swap_b32 v45, v45
	v_cmp_lt_i32_e64 s[4:5], 1, v233
	v_cmp_eq_u32_e64 s[6:7], 1, v233
	v_bfrev_b32_e32 v239, 1
	s_nop 0
	v_cndmask_b32_e64 v239, v239, 0, s[6:7]
	v_mul_f32_e32 v46, v38, v142
	v_mul_f32_e32 v47, v138, v47
	v_xor_b32_e32 v47, v239, v47
	v_add_f32_e32 v46, v46, v47
	v_cndmask_b32_e64 v38, v46, v38, s[4:5]
	v_mul_f32_e32 v44, v34, v134
	v_mul_f32_e32 v45, v130, v45
	v_xor_b32_e32 v45, v239, v45
	v_add_f32_e32 v44, v44, v45
	v_cndmask_b32_e64 v34, v44, v34, s[4:5]
	s_waitcnt lgkmcnt(0)
	v_mov_b32_e32 v47, v39
	v_mov_b32_e32 v45, v35
	s_nop 0
	v_permlane16_swap_b32 v47, v47
	v_permlane16_swap_b32 v45, v45
	v_cmp_lt_i32_e64 s[4:5], 1, v233
	v_cmp_eq_u32_e64 s[6:7], 1, v233
	v_bfrev_b32_e32 v239, 1
	s_nop 0
	v_cndmask_b32_e64 v239, v239, 0, s[6:7]
	v_mul_f32_e32 v44, v143, v39
	v_xor_b32_e32 v238, v239, v139
	v_fma_f32 v47, v238, v47, v44
	v_cndmask_b32_e64 v39, v47, v39, s[4:5]
	v_mul_f32_e32 v46, v135, v35
	v_xor_b32_e32 v238, v239, v131
	v_fma_f32 v45, v238, v45, v46
	v_cndmask_b32_e64 v35, v45, v35, s[4:5]
	s_waitcnt lgkmcnt(0)
	v_mov_b32_e32 v47, v40
	v_mov_b32_e32 v45, v36
	s_nop 0
	v_permlane16_swap_b32 v47, v47
	v_permlane16_swap_b32 v45, v45
	v_cmp_lt_i32_e64 s[4:5], 1, v233
	v_cmp_eq_u32_e64 s[6:7], 1, v233
	v_bfrev_b32_e32 v239, 1
	s_nop 0
	v_cndmask_b32_e64 v239, v239, 0, s[6:7]
	v_mul_f32_e32 v47, v140, v47
	v_xor_b32_e32 v47, v239, v47
	v_fma_f32 v46, v144, v40, v47
	v_cndmask_b32_e64 v40, v46, v40, s[4:5]
	v_mul_f32_e32 v45, v132, v45
	v_xor_b32_e32 v45, v239, v45
	v_fma_f32 v44, v136, v36, v45
	v_cndmask_b32_e64 v36, v44, v36, s[4:5]
	s_waitcnt lgkmcnt(0)
	v_mov_b32_e32 v47, v41
	v_mov_b32_e32 v45, v37
	s_nop 0
	v_permlane16_swap_b32 v47, v47
	v_permlane16_swap_b32 v45, v45
	v_cmp_lt_i32_e64 s[4:5], 1, v233
	v_cmp_eq_u32_e64 s[6:7], 1, v233
	v_bfrev_b32_e32 v239, 1
	s_nop 0
	v_cndmask_b32_e64 v239, v239, 0, s[6:7]
	v_mul_f32_e32 v47, v141, v47
	v_xor_b32_e32 v47, v239, v47
	v_fma_f32 v46, v145, v41, v47
	v_cndmask_b32_e64 v41, v46, v41, s[4:5]
	v_mul_f32_e32 v45, v133, v45
	v_xor_b32_e32 v45, v239, v45
	v_fma_f32 v44, v137, v37, v45
	v_cndmask_b32_e64 v37, v44, v37, s[4:5]

.LBB0_627:
	s_waitcnt vmcnt(0)
	v_pk_mul_f32 v[32:33], v[32:33], v[192:193] op_sel_hi:[1,0]
	v_pk_mul_f32 v[30:31], v[30:31], v[192:193] op_sel_hi:[1,0]
	v_pk_mul_f32 v[28:29], v[28:29], v[192:193] op_sel_hi:[1,0]
	s_and_b64 vcc, exec, s[42:43]
	v_pk_mul_f32 v[26:27], v[26:27], v[192:193] op_sel_hi:[1,0]
	s_cbranch_vccnz .LBB0_653
	v_and_b32_e32 v35, 64, v226
	v_xor_b32_e32 v34, 16, v226
	v_add_u32_e32 v35, 64, v35
	v_cmp_lt_i32_e32 vcc, v34, v35
	s_nop 1
	v_cndmask_b32_e32 v34, v226, v34, vcc
	v_lshlrev_b32_e32 v38, 2, v34
	v_mov_b32_e32 v37, v30
	v_mov_b32_e32 v35, v26
	s_nop 0
	v_permlane16_swap_b32 v37, v37
	v_permlane16_swap_b32 v35, v35
	v_cmp_lt_i32_e64 s[4:5], 1, v233
	v_cmp_eq_u32_e64 s[6:7], 1, v233
	v_bfrev_b32_e32 v239, 1
	s_nop 0
	v_cndmask_b32_e64 v239, v239, 0, s[6:7]
	v_mul_f32_e32 v36, v30, v126
	v_mul_f32_e32 v37, v122, v37
	v_xor_b32_e32 v37, v239, v37
	v_add_f32_e32 v36, v36, v37
	v_cndmask_b32_e64 v30, v36, v30, s[4:5]
	v_mul_f32_e32 v34, v26, v118
	v_mul_f32_e32 v35, v114, v35
	v_xor_b32_e32 v35, v239, v35
	v_add_f32_e32 v34, v34, v35
	v_cndmask_b32_e64 v26, v34, v26, s[4:5]
	s_waitcnt lgkmcnt(0)
	v_mov_b32_e32 v37, v31
	v_mov_b32_e32 v35, v27
	s_nop 0
	v_permlane16_swap_b32 v37, v37
	v_permlane16_swap_b32 v35, v35
	v_cmp_lt_i32_e64 s[4:5], 1, v233
	v_cmp_eq_u32_e64 s[6:7], 1, v233
	v_bfrev_b32_e32 v239, 1
	s_nop 0
	v_cndmask_b32_e64 v239, v239, 0, s[6:7]
	v_mul_f32_e32 v34, v127, v31
	v_xor_b32_e32 v238, v239, v123
	v_fma_f32 v37, v238, v37, v34
	v_cndmask_b32_e64 v31, v37, v31, s[4:5]
	v_mul_f32_e32 v36, v119, v27
	v_xor_b32_e32 v238, v239, v115
	v_fma_f32 v35, v238, v35, v36
	v_cndmask_b32_e64 v27, v35, v27, s[4:5]
	s_waitcnt lgkmcnt(0)
	v_mov_b32_e32 v37, v32
	v_mov_b32_e32 v35, v28
	s_nop 0
	v_permlane16_swap_b32 v37, v37
	v_permlane16_swap_b32 v35, v35
	v_cmp_lt_i32_e64 s[4:5], 1, v233
	v_cmp_eq_u32_e64 s[6:7], 1, v233
	v_bfrev_b32_e32 v239, 1
	s_nop 0
	v_cndmask_b32_e64 v239, v239, 0, s[6:7]
	v_mul_f32_e32 v37, v124, v37
	v_xor_b32_e32 v37, v239, v37
	v_fma_f32 v36, v128, v32, v37
	v_cndmask_b32_e64 v32, v36, v32, s[4:5]
	v_mul_f32_e32 v35, v116, v35
	v_xor_b32_e32 v35, v239, v35
	v_fma_f32 v34, v120, v28, v35
	v_cndmask_b32_e64 v28, v34, v28, s[4:5]
	s_waitcnt lgkmcnt(0)
	v_mov_b32_e32 v37, v33
	v_mov_b32_e32 v35, v29
	s_nop 0
	v_permlane16_swap_b32 v37, v37
	v_permlane16_swap_b32 v35, v35
	v_cmp_lt_i32_e64 s[4:5], 1, v233
	v_cmp_eq_u32_e64 s[6:7], 1, v233
	v_bfrev_b32_e32 v239, 1
	s_nop 0
	v_cndmask_b32_e64 v239, v239, 0, s[6:7]
	v_mul_f32_e32 v37, v125, v37
	v_xor_b32_e32 v37, v239, v37
	v_fma_f32 v36, v129, v33, v37
	v_cndmask_b32_e64 v33, v36, v33, s[4:5]
	v_mul_f32_e32 v35, v117, v35
	v_xor_b32_e32 v35, v239, v35
	v_fma_f32 v34, v121, v29, v35
	v_cndmask_b32_e64 v29, v34, v29, s[4:5]
.LBB0_653:
	s_waitcnt lgkmcnt(0)
	v_pk_mul_f32 v[34:35], v[30:31], s[36:37] op_sel_hi:[1,0]
	v_pk_mul_f32 v[38:39], v[26:27], s[36:37] op_sel_hi:[1,0]
	v_pk_mul_f32 v[36:37], v[32:33], s[36:37] op_sel_hi:[1,0]
	v_pk_mul_f32 v[40:41], v[28:29], s[36:37] op_sel_hi:[1,0]
	v_cndmask_b32_e64 v30, v30, v34, s[40:41]
	v_cndmask_b32_e64 v26, v26, v38, s[40:41]
	v_cndmask_b32_e64 v27, v27, v39, s[40:41]
	v_cndmask_b32_e64 v32, v32, v36, s[40:41]
	v_cndmask_b32_e64 v33, v33, v37, s[40:41]
	v_cndmask_b32_e64 v31, v31, v35, s[40:41]
	v_cndmask_b32_e64 v34, v28, v40, s[40:41]
	v_cndmask_b32_e64 v35, v29, v41, s[40:41]
	v_cvt_pk_bf16_f32 v28, v30, v31
	v_cvt_pk_bf16_f32 v29, v32, v33
	v_cvt_pk_bf16_f32 v30, v26, v27
	v_mov_b64_e32 v[26:27], s[62:63]
	s_movk_i32 s4, 0x1200
	v_mad_i64_i32 v[26:27], s[4:5], v190, s4, v[26:27]
	v_lshl_add_u64 v[32:33], v[0:1], 1, v[26:27]
	s_movk_i32 s4, 0xf000
	v_add_co_u32_e32 v32, vcc, s4, v32
	v_mov_b32_e32 v193, v192
	s_nop 0
	v_addc_co_u32_e32 v33, vcc, -1, v33, vcc
	v_cvt_pk_bf16_f32 v31, v34, v35
	flat_store_dwordx4 v[32:33], v[28:31] nt
	v_pk_mul_f32 v[22:23], v[22:23], v[192:193]
	s_and_b64 vcc, exec, s[46:47]
	v_mov_b32_e32 v28, v192
	v_mov_b32_e32 v29, v192
	v_pk_mul_f32 v[24:25], v[24:25], v[28:29]
	v_pk_mul_f32 v[20:21], v[20:21], v[28:29]
	v_pk_mul_f32 v[18:19], v[18:19], v[192:193]
	s_cbranch_vccnz .LBB0_679
	v_and_b32_e32 v29, 64, v226
	v_xor_b32_e32 v28, 16, v226
	v_add_u32_e32 v29, 64, v29
	v_cmp_lt_i32_e32 vcc, v28, v29
	s_nop 1
	v_cndmask_b32_e32 v28, v226, v28, vcc
	v_lshlrev_b32_e32 v32, 2, v28
	v_mov_b32_e32 v31, v22
	v_mov_b32_e32 v29, v18
	s_nop 0
	v_permlane16_swap_b32 v31, v31
	v_permlane16_swap_b32 v29, v29
	v_cmp_lt_i32_e64 s[4:5], 1, v233
	v_cmp_eq_u32_e64 s[6:7], 1, v233
	v_bfrev_b32_e32 v239, 1
	s_nop 0
	v_cndmask_b32_e64 v239, v239, 0, s[6:7]
	v_mul_f32_e32 v30, v22, v126
	v_mul_f32_e32 v31, v122, v31
	v_xor_b32_e32 v31, v239, v31
	v_add_f32_e32 v30, v30, v31
	v_cndmask_b32_e64 v22, v30, v22, s[4:5]
	v_mul_f32_e32 v28, v18, v118
	v_mul_f32_e32 v29, v114, v29
	v_xor_b32_e32 v29, v239, v29
	v_add_f32_e32 v28, v28, v29
	v_cndmask_b32_e64 v18, v28, v18, s[4:5]
	s_waitcnt lgkmcnt(0)
	v_mov_b32_e32 v31, v23
	v_mov_b32_e32 v29, v19
	s_nop 0
	v_permlane16_swap_b32 v31, v31
	v_permlane16_swap_b32 v29, v29
	v_cmp_lt_i32_e64 s[4:5], 1, v233
	v_cmp_eq_u32_e64 s[6:7], 1, v233
	v_bfrev_b32_e32 v239, 1
	s_nop 0
	v_cndmask_b32_e64 v239, v239, 0, s[6:7]
	v_mul_f32_e32 v28, v127, v23
	v_xor_b32_e32 v238, v239, v123
	v_fma_f32 v31, v238, v31, v28
	v_cndmask_b32_e64 v23, v31, v23, s[4:5]
	v_mul_f32_e32 v30, v119, v19
	v_xor_b32_e32 v238, v239, v115
	v_fma_f32 v29, v238, v29, v30
	v_cndmask_b32_e64 v19, v29, v19, s[4:5]
	s_waitcnt lgkmcnt(0)
	v_mov_b32_e32 v31, v24
	v_mov_b32_e32 v29, v20
	s_nop 0
	v_permlane16_swap_b32 v31, v31
	v_permlane16_swap_b32 v29, v29
	v_cmp_lt_i32_e64 s[4:5], 1, v233
	v_cmp_eq_u32_e64 s[6:7], 1, v233
	v_bfrev_b32_e32 v239, 1
	s_nop 0
	v_cndmask_b32_e64 v239, v239, 0, s[6:7]
	v_mul_f32_e32 v31, v124, v31
	v_xor_b32_e32 v31, v239, v31
	v_fma_f32 v30, v128, v24, v31
	v_cndmask_b32_e64 v24, v30, v24, s[4:5]
	v_mul_f32_e32 v29, v116, v29
	v_xor_b32_e32 v29, v239, v29
	v_fma_f32 v28, v120, v20, v29
	v_cndmask_b32_e64 v20, v28, v20, s[4:5]
	s_waitcnt lgkmcnt(0)
	v_mov_b32_e32 v31, v25
	v_mov_b32_e32 v29, v21
	s_nop 0
	v_permlane16_swap_b32 v31, v31
	v_permlane16_swap_b32 v29, v29
	v_cmp_lt_i32_e64 s[4:5], 1, v233
	v_cmp_eq_u32_e64 s[6:7], 1, v233
	v_bfrev_b32_e32 v239, 1
	s_nop 0
	v_cndmask_b32_e64 v239, v239, 0, s[6:7]
	v_mul_f32_e32 v31, v125, v31
	v_xor_b32_e32 v31, v239, v31
	v_fma_f32 v30, v129, v25, v31
	v_cndmask_b32_e64 v25, v30, v25, s[4:5]
	v_mul_f32_e32 v29, v117, v29
	v_xor_b32_e32 v29, v239, v29
	v_fma_f32 v28, v121, v21, v29
	v_cndmask_b32_e64 v21, v28, v21, s[4:5]
.LBB0_679:
	s_waitcnt lgkmcnt(0)
	v_pk_mul_f32 v[28:29], v[22:23], s[36:37] op_sel_hi:[1,0]
	v_pk_mul_f32 v[32:33], v[18:19], s[36:37] op_sel_hi:[1,0]
	v_pk_mul_f32 v[34:35], v[20:21], s[36:37] op_sel_hi:[1,0]
	v_cndmask_b32_e64 v22, v22, v28, s[44:45]
	v_cndmask_b32_e64 v23, v23, v29, s[44:45]
	v_cndmask_b32_e64 v28, v20, v34, s[44:45]
	v_cndmask_b32_e64 v20, v18, v32, s[44:45]
	v_cvt_pk_bf16_f32 v18, v22, v23
	v_lshl_add_u64 v[22:23], v[214:215], 1, v[26:27]
	s_movk_i32 s4, 0xf100
	v_add_co_u32_e32 v22, vcc, s4, v22
	v_pk_mul_f32 v[30:31], v[24:25], s[36:37] op_sel_hi:[1,0]
	s_nop 0
	v_addc_co_u32_e32 v23, vcc, -1, v23, vcc
	v_cndmask_b32_e64 v21, v21, v35, s[44:45]
	v_pk_mul_f32 v[16:17], v[16:17], v[176:177] op_sel_hi:[1,0]
	v_pk_mul_f32 v[14:15], v[14:15], v[176:177] op_sel_hi:[1,0]
	v_pk_mul_f32 v[12:13], v[12:13], v[176:177] op_sel_hi:[1,0]
	s_and_b64 vcc, exec, s[42:43]
	v_pk_mul_f32 v[10:11], v[10:11], v[176:177] op_sel_hi:[1,0]
	v_cndmask_b32_e64 v24, v24, v30, s[44:45]
	v_cndmask_b32_e64 v25, v25, v31, s[44:45]
	v_cndmask_b32_e64 v29, v19, v33, s[44:45]
	v_cvt_pk_bf16_f32 v19, v24, v25
	v_cvt_pk_bf16_f32 v20, v20, v29
	v_cvt_pk_bf16_f32 v21, v28, v21
	flat_store_dwordx4 v[22:23], v[18:21] nt
	s_cbranch_vccnz .LBB0_705
	s_nop 0
	v_and_b32_e32 v19, 64, v226
	v_xor_b32_e32 v18, 16, v226
	v_add_u32_e32 v19, 64, v19
	v_cmp_lt_i32_e32 vcc, v18, v19
	s_nop 1
	v_cndmask_b32_e32 v18, v226, v18, vcc
	v_lshlrev_b32_e32 v22, 2, v18
	v_mov_b32_e32 v21, v14
	v_mov_b32_e32 v19, v10
	s_nop 0
	v_permlane16_swap_b32 v21, v21
	v_permlane16_swap_b32 v19, v19
	v_cmp_lt_i32_e64 s[4:5], 1, v233
	v_cmp_eq_u32_e64 s[6:7], 1, v233
	v_bfrev_b32_e32 v239, 1
	s_nop 0
	v_cndmask_b32_e64 v239, v239, 0, s[6:7]
	v_mul_f32_e32 v20, v14, v110
	v_mul_f32_e32 v21, v106, v21
	v_xor_b32_e32 v21, v239, v21
	v_add_f32_e32 v20, v20, v21
	v_cndmask_b32_e64 v14, v20, v14, s[4:5]
	v_mul_f32_e32 v18, v10, v102
	v_mul_f32_e32 v19, v98, v19
	v_xor_b32_e32 v19, v239, v19
	v_add_f32_e32 v18, v18, v19
	v_cndmask_b32_e64 v10, v18, v10, s[4:5]
	s_waitcnt lgkmcnt(0)
	v_mov_b32_e32 v21, v15
	v_mov_b32_e32 v19, v11
	s_nop 0
	v_permlane16_swap_b32 v21, v21
	v_permlane16_swap_b32 v19, v19
	v_cmp_lt_i32_e64 s[4:5], 1, v233
	v_cmp_eq_u32_e64 s[6:7], 1, v233
	v_bfrev_b32_e32 v239, 1
	s_nop 0
	v_cndmask_b32_e64 v239, v239, 0, s[6:7]
	v_mul_f32_e32 v18, v111, v15
	v_xor_b32_e32 v238, v239, v107
	v_fma_f32 v21, v238, v21, v18
	v_cndmask_b32_e64 v15, v21, v15, s[4:5]
	v_mul_f32_e32 v20, v103, v11
	v_xor_b32_e32 v238, v239, v99
	v_fma_f32 v19, v238, v19, v20
	v_cndmask_b32_e64 v11, v19, v11, s[4:5]
	s_waitcnt lgkmcnt(0)
	v_mov_b32_e32 v21, v16
	v_mov_b32_e32 v19, v12
	s_nop 0
	v_permlane16_swap_b32 v21, v21
	v_permlane16_swap_b32 v19, v19
	v_cmp_lt_i32_e64 s[4:5], 1, v233
	v_cmp_eq_u32_e64 s[6:7], 1, v233
	v_bfrev_b32_e32 v239, 1
	s_nop 0
	v_cndmask_b32_e64 v239, v239, 0, s[6:7]
	v_mul_f32_e32 v21, v108, v21
	v_xor_b32_e32 v21, v239, v21
	v_fma_f32 v20, v112, v16, v21
	v_cndmask_b32_e64 v16, v20, v16, s[4:5]
	v_mul_f32_e32 v19, v100, v19
	v_xor_b32_e32 v19, v239, v19
	v_fma_f32 v18, v104, v12, v19
	v_cndmask_b32_e64 v12, v18, v12, s[4:5]
	s_waitcnt lgkmcnt(0)
	v_mov_b32_e32 v21, v17
	v_mov_b32_e32 v19, v13
	s_nop 0
	v_permlane16_swap_b32 v21, v21
	v_permlane16_swap_b32 v19, v19
	v_cmp_lt_i32_e64 s[4:5], 1, v233
	v_cmp_eq_u32_e64 s[6:7], 1, v233
	v_bfrev_b32_e32 v239, 1
	s_nop 0
	v_cndmask_b32_e64 v239, v239, 0, s[6:7]
	v_mul_f32_e32 v21, v109, v21
	v_xor_b32_e32 v21, v239, v21
	v_fma_f32 v20, v113, v17, v21
	v_cndmask_b32_e64 v17, v20, v17, s[4:5]
	v_mul_f32_e32 v19, v101, v19
	v_xor_b32_e32 v19, v239, v19
	v_fma_f32 v18, v105, v13, v19
	v_cndmask_b32_e64 v13, v18, v13, s[4:5]
.LBB0_705:
	s_waitcnt lgkmcnt(0)
	v_pk_mul_f32 v[18:19], v[14:15], s[36:37] op_sel_hi:[1,0]
	v_pk_mul_f32 v[22:23], v[10:11], s[36:37] op_sel_hi:[1,0]
	v_pk_mul_f32 v[20:21], v[16:17], s[36:37] op_sel_hi:[1,0]
	v_pk_mul_f32 v[24:25], v[12:13], s[36:37] op_sel_hi:[1,0]
	v_cndmask_b32_e64 v14, v14, v18, s[40:41]
	v_cndmask_b32_e64 v10, v10, v22, s[40:41]
	v_cndmask_b32_e64 v11, v11, v23, s[40:41]
	v_cndmask_b32_e64 v16, v16, v20, s[40:41]
	v_cndmask_b32_e64 v17, v17, v21, s[40:41]
	v_cndmask_b32_e64 v15, v15, v19, s[40:41]
	v_cndmask_b32_e64 v18, v12, v24, s[40:41]
	v_cndmask_b32_e64 v19, v13, v25, s[40:41]
	v_cvt_pk_bf16_f32 v12, v14, v15
	v_cvt_pk_bf16_f32 v13, v16, v17
	v_cvt_pk_bf16_f32 v14, v10, v11
	v_mov_b64_e32 v[10:11], s[62:63]
	s_movk_i32 s4, 0x1200
	v_mad_i64_i32 v[10:11], s[4:5], v174, s4, v[10:11]
	v_lshl_add_u64 v[16:17], v[0:1], 1, v[10:11]
	s_movk_i32 s4, 0xf000
	v_add_co_u32_e32 v16, vcc, s4, v16
	v_mov_b32_e32 v177, v176
	s_nop 0
	v_addc_co_u32_e32 v17, vcc, -1, v17, vcc
	v_cvt_pk_bf16_f32 v15, v18, v19
	flat_store_dwordx4 v[16:17], v[12:15] nt
	v_pk_mul_f32 v[6:7], v[6:7], v[176:177]
	s_and_b64 vcc, exec, s[46:47]
	v_mov_b32_e32 v12, v176
	v_mov_b32_e32 v13, v176
	v_pk_mul_f32 v[8:9], v[8:9], v[12:13]
	v_pk_mul_f32 v[4:5], v[4:5], v[12:13]
	v_pk_mul_f32 v[2:3], v[2:3], v[176:177]
	s_cbranch_vccnz .LBB0_731
	v_and_b32_e32 v12, 64, v226
	v_xor_b32_e32 v0, 16, v226
	v_add_u32_e32 v12, 64, v12
	v_cmp_lt_i32_e32 vcc, v0, v12
	s_nop 1
	v_cndmask_b32_e32 v0, v226, v0, vcc
	v_lshlrev_b32_e32 v0, 2, v0
	v_mov_b32_e32 v15, v6
	v_mov_b32_e32 v13, v2
	s_nop 0
	v_permlane16_swap_b32 v15, v15
	v_permlane16_swap_b32 v13, v13
	v_cmp_lt_i32_e64 s[4:5], 1, v233
	v_cmp_eq_u32_e64 s[6:7], 1, v233
	v_bfrev_b32_e32 v239, 1
	s_nop 0
	v_cndmask_b32_e64 v239, v239, 0, s[6:7]
	v_mul_f32_e32 v14, v6, v110
	v_mul_f32_e32 v15, v106, v15
	v_xor_b32_e32 v15, v239, v15
	v_add_f32_e32 v14, v14, v15
	v_cndmask_b32_e64 v6, v14, v6, s[4:5]
	v_mul_f32_e32 v12, v2, v102
	v_mul_f32_e32 v13, v98, v13
	v_xor_b32_e32 v13, v239, v13
	v_add_f32_e32 v12, v12, v13
	v_cndmask_b32_e64 v2, v12, v2, s[4:5]
	s_waitcnt lgkmcnt(0)
	v_mov_b32_e32 v15, v7
	v_mov_b32_e32 v13, v3
	s_nop 0
	v_permlane16_swap_b32 v15, v15
	v_permlane16_swap_b32 v13, v13
	v_cmp_lt_i32_e64 s[4:5], 1, v233
	v_cmp_eq_u32_e64 s[6:7], 1, v233
	v_bfrev_b32_e32 v239, 1
	s_nop 0
	v_cndmask_b32_e64 v239, v239, 0, s[6:7]
	v_mul_f32_e32 v12, v111, v7
	v_xor_b32_e32 v238, v239, v107
	v_fma_f32 v15, v238, v15, v12
	v_cndmask_b32_e64 v7, v15, v7, s[4:5]
	v_mul_f32_e32 v14, v103, v3
	v_xor_b32_e32 v238, v239, v99
	v_fma_f32 v13, v238, v13, v14
	v_cndmask_b32_e64 v3, v13, v3, s[4:5]
	s_waitcnt lgkmcnt(0)
	v_mov_b32_e32 v15, v8
	v_mov_b32_e32 v13, v4
	s_nop 0
	v_permlane16_swap_b32 v15, v15
	v_permlane16_swap_b32 v13, v13
	v_cmp_lt_i32_e64 s[4:5], 1, v233
	v_cmp_eq_u32_e64 s[6:7], 1, v233
	v_bfrev_b32_e32 v239, 1
	s_nop 0
	v_cndmask_b32_e64 v239, v239, 0, s[6:7]
	v_mul_f32_e32 v15, v108, v15
	v_xor_b32_e32 v15, v239, v15
	v_fma_f32 v14, v112, v8, v15
	v_cndmask_b32_e64 v8, v14, v8, s[4:5]
	v_mul_f32_e32 v13, v100, v13
	v_xor_b32_e32 v13, v239, v13
	v_fma_f32 v12, v104, v4, v13
	v_cndmask_b32_e64 v4, v12, v4, s[4:5]
	s_waitcnt lgkmcnt(0)
	v_mov_b32_e32 v15, v9
	v_mov_b32_e32 v13, v5
	s_nop 0
	v_permlane16_swap_b32 v15, v15
	v_permlane16_swap_b32 v13, v13
	v_cmp_lt_i32_e64 s[4:5], 1, v233
	v_cmp_eq_u32_e64 s[6:7], 1, v233
	v_bfrev_b32_e32 v239, 1
	s_nop 0
	v_cndmask_b32_e64 v239, v239, 0, s[6:7]
	v_mul_f32_e32 v15, v109, v15
	v_xor_b32_e32 v15, v239, v15
	v_fma_f32 v14, v113, v9, v15
	v_cndmask_b32_e64 v9, v14, v9, s[4:5]
	v_mul_f32_e32 v13, v101, v13
	v_xor_b32_e32 v13, v239, v13
	v_fma_f32 v12, v105, v5, v13
	v_cndmask_b32_e64 v5, v12, v5, s[4:5]
